# grid-barrier poll loops: s_sleep 16 between counter polls
# baseline (speedup 1.0000x reference)
.LBB0_141:
	s_sleep 16
	global_load_dword v0, v153, s[4:5] sc1
	s_waitcnt vmcnt(0)
	v_subrev_u32_e32 v0, s16, v0
	v_cmp_gt_i32_e32 vcc, 0, v0
	s_cbranch_vccnz .LBB0_141
	s_branch .LBB0_110

.LBB0_209:
	s_sleep 16
	global_load_dword v0, v153, s[4:5] sc1
	s_waitcnt vmcnt(0)
	v_subrev_u32_e32 v0, s22, v0
	v_cmp_gt_i32_e32 vcc, 0, v0
	s_cbranch_vccnz .LBB0_209

.LBB0_322:
	s_sleep 16
	global_load_dword v0, v153, s[4:5] sc1
	s_waitcnt vmcnt(0)
	v_subrev_u32_e32 v0, s62, v0
	v_cmp_gt_i32_e32 vcc, 0, v0
	s_cbranch_vccnz .LBB0_322

.LBB0_996:
	s_sleep 16
	global_load_dword v0, v153, s[4:5] sc1
	s_waitcnt vmcnt(0)
	v_subrev_u32_e32 v0, s6, v0
	v_cmp_gt_i32_e32 vcc, 0, v0
	s_cbranch_vccnz .LBB0_996

.LBB0_1119:
	s_sleep 16
	global_load_dword v0, v153, s[4:5] sc1
	s_waitcnt vmcnt(0)
	v_subrev_u32_e32 v0, s71, v0
	v_cmp_gt_i32_e32 vcc, 0, v0
	s_cbranch_vccnz .LBB0_1119
